# attention: static s_setprio 1 for the staggered (second) wave group
# speedup vs baseline: 1.0138x; 1.0138x over previous
; __device__ __forceinline__ void attn_phase(const Ctx& c, const Params& p, int o, int first, int cidx) {
;     ...
;         for (int kt = 0; kt < ntile; ++kt) { const int kv0 = kt * 64; const int buf = kt & 1;
;             if (kt + 1 < ntile) { const int kn = kv0 + 64;
;                 rk0 = *(const u32x4*)(kg + (size_t)(kn + k0row) * 768 + 8 * k0ch); if (k1on) rk1 = *(const u32x4*)(kg + (size_t)(kn + k1row) * 768 + 8 * k1ch); rv = *(const u32x4*)(vg + (size_t)vrow * T_ + kn + 8 * vch); }
.Lsb_loop:
	s_setprio 1
	s_add_i32 s31, s10, 1
	s_cmp_lt_u32 s31, s27
	s_cselect_b64 s[2:3], -1, 0
	s_cmp_ge_u32 s31, s27
	s_cbranch_scc1 .Lsb_124
	v_add_u32_e32 v250, s42, v133
	v_mad_i64_i32 v[248:249], s[18:19], v250, s50, v[120:121]
	s_waitcnt vmcnt(0)
	global_load_dwordx4 v[90:93], v[248:249], off
	s_and_saveexec_b64 s[18:19], s[6:7]
	s_cbranch_execz .Lsb_123
	v_add_u32_e32 v250, s42, v132
	v_mad_i64_i32 v[248:249], s[34:35], v250, s50, v[122:123]
	global_load_dwordx4 v[94:97], v[248:249], off

; __device__ __forceinline__ void attn_phase(const Ctx& c, const Params& p, int o, int first, int cidx) {
;     ...
;             __syncthreads();
;         }
;         float l; { auto rr = __builtin_amdgcn_permlane32_swap(asu(lrun), asu(lrun), false, false); l = asf(rr[0]) + asf(rr[1]); }
.Lsb_fin2:
	s_setprio 0
	s_branch .LBB0_110
